# P4 first-unit-phase block: second counted wait vmcnt(8) -> vmcnt(14): it only needs tiles issued before the previous epilogue, so the previous unit's last stores are no longer waited for
# baseline (speedup 1.0000x reference)
;     __device__ __forceinline__ bool next(int i, Unit& u) const { if (i >= count) return false; const int L = first + i; u.pm = L / nN; u.pn = L % nN; return true; }
; #define PG8_STAGE(bufoff, gbase, voff) do { if constexpr (ABL & 1) break; glds16s<(bufoff)>((voff)[0], (const void*)(gbase), ldsbw); glds16s<(bufoff) + 8192>((voff)[1], (const void*)(gbase), ldsbw); } while (0)
; #define PG8_LDA(dst, b, h) do { if constexpr (ABL & 4) break; _Pragma("unroll") for (int m = 0; m < 4; ++m) _Pragma("unroll") for (int k = 0; k < 2; ++k) dst[m][k] = *(const LAS f16x8*)(lds + PG8_SA(b, h) + aoff + m * 2048 + k * 1024); } while (0)
; #define PG8_LDB(dst, b, h) do { if constexpr (ABL & 4) break; _Pragma("unroll") for (int n = 0; n < 2; ++n) _Pragma("unroll") for (int k = 0; k < 2; ++k) dst[n][k] = *(const LAS f16x8*)(lds + PG8_SB(b, h) + boff + n * 2048 + k * 1024); } while (0)
; #define PG8_MMAF(ai, bj, At, Bt) do { if (t == 0) PG8_MMA0(ai, bj, At, Bt); else PG8_MMA(ai, bj, At, Bt); } while (0)
; #define PG8_WAIT_V(n) asm volatile("s_waitcnt vmcnt(" #n ")" ::: "memory")
; #define PG8_BAR __builtin_amdgcn_s_barrier()
;     ...
;         const bool has_next = S.next(ui + 1, nxt);
;         const char* nA = has_next ? (const char*)g.A + (size_t)nxt.pm * tstep : cA; const char* nB = has_next ? (const char*)g.Bt + (size_t)nxt.pn * tstep : cB;
;         for (int t = 0; t < nt; t += 2) {
;             const bool last = (t == nt - 2);
;             const char* a1 = cA + (size_t)(t + 1) * kstep;
;             const char* a2 = last ? nA : cA + (size_t)(t + 2) * kstep; const char* b2 = last ? nB : cB + (size_t)(t + 2) * kstep;
;             const char* a3 = a2 + kstep; const char* b3 = b2 + kstep;
;             if (last && has_next) S.a_ready(nxt);
;             if constexpr (SP2) {
;             PG8_LDB(B0, 0, 0); PG8_LDB(B1, 0, 1); PG8_SCHED; PG8_LDA(At, 0, 0); PG8_STAGE(PG8_SA(1, 1), a1 + hstep, voffA);
;             PG8_WAIT_V(8); PG8_WAIT_L(0); PG8_BAR; PG8_MMAF(0, 0, At, B0); PG8_MMAF(0, 1, At, B1); PG8_BAR; PG8_SCHED;
;             const bool fin = last && !has_next;
;             PG8_LDA(At, 0, 1); if (!fin) { PG8_STAGE(PG8_SB(0, 0), b2, voffB); PG8_STAGE(PG8_SB(0, 1), b2 + hstep, voffB); PG8_STAGE(PG8_SA(0, 0), a2, voffA); }
;             if (!fin) PG8_WAIT_V(8); else PG8_WAIT_V(2); PG8_WAIT_L(0); PG8_BAR; PG8_MMAF(1, 0, At, B0); PG8_MMAF(1, 1, At, B1); PG8_BAR; PG8_SCHED;
.LBB0_841:
	s_ashr_i32 s41, s40, 31
	s_lshl_b64 s[24:25], s[40:41], 19
	s_add_u32 s42, s74, s24
	s_addc_u32 s43, s75, s25
	s_and_b64 s[24:25], exec, s[4:5]
	ds_read_b128 v[2:5], v210
	ds_read_b128 v[6:9], v210 offset:1024
	ds_read_b128 v[10:13], v210 offset:2048
	ds_read_b128 v[14:17], v210 offset:3072
	ds_read_b128 v[18:21], v211
	ds_read_b128 v[22:25], v211 offset:1024
	ds_read_b128 v[26:29], v211 offset:2048
	ds_read_b128 v[30:33], v211 offset:3072
	s_cselect_b32 s41, s9, s43
	s_cselect_b32 s51, s8, s42
	s_ashr_i32 s39, s38, 31
	s_lshl_b64 s[24:25], s[38:39], 19
	s_add_u32 s44, s58, s24
	s_addc_u32 s45, s59, s25
	s_and_b64 s[24:25], exec, s[4:5]
	s_cselect_b32 s39, s7, s45
	s_cselect_b32 s52, s6, s44
	s_add_u32 s48, s8, 0x100
	s_addc_u32 s49, s9, 0
	s_add_u32 s54, s6, 0x100
	s_addc_u32 s55, s7, 0
	s_add_u32 s24, s8, 0x180
	s_addc_u32 s25, s9, 0
	ds_read_b128 v[34:37], v212
	ds_read_b128 v[38:41], v212 offset:1024
	ds_read_b128 v[42:45], v212 offset:2048
	ds_read_b128 v[46:49], v212 offset:3072
	ds_read_b128 v[50:53], v212 offset:4096
	ds_read_b128 v[54:57], v212 offset:5120
	ds_read_b128 v[58:61], v212 offset:6144
	ds_read_b128 v[62:65], v212 offset:7168
	s_add_u32 s26, s6, 0x180
	s_addc_u32 s27, s7, 0
	s_add_u32 s56, s8, 0x40080
	s_addc_u32 s57, s9, 0
	s_add_u32 m0, s14, 0xc000
	s_nop 0
	global_load_lds_dwordx4 v206, s[56:57]
	s_nop 0
	s_add_u32 m0, s14, 0xe000
	s_nop 0
	global_load_lds_dwordx4 v208, s[56:57]
	s_waitcnt vmcnt(8)
	s_waitcnt lgkmcnt(0)
	s_barrier
	v_mfma_f32_16x16x32_f16 v[90:93], v[2:5], v[58:61], 0
	s_setprio 1
	v_mfma_f32_16x16x32_f16 v[94:97], v[6:9], v[62:65], v[90:93]
	v_mfma_f32_16x16x32_f16 v[66:69], v[2:5], v[34:37], 0
	v_mfma_f32_16x16x32_f16 v[66:69], v[6:9], v[38:41], v[66:69]
	v_mfma_f32_16x16x32_f16 v[70:73], v[10:13], v[34:37], 0
	v_mfma_f32_16x16x32_f16 v[70:73], v[14:17], v[38:41], v[70:73]
	v_mfma_f32_16x16x32_f16 v[74:77], v[2:5], v[42:45], 0
	v_mfma_f32_16x16x32_f16 v[74:77], v[6:9], v[46:49], v[74:77]
	v_mfma_f32_16x16x32_f16 v[78:81], v[10:13], v[42:45], 0
	v_mfma_f32_16x16x32_f16 v[78:81], v[14:17], v[46:49], v[78:81]
	v_mfma_f32_16x16x32_f16 v[82:85], v[2:5], v[50:53], 0
	v_mfma_f32_16x16x32_f16 v[82:85], v[6:9], v[54:57], v[82:85]
	v_mfma_f32_16x16x32_f16 v[86:89], v[10:13], v[50:53], 0
	v_mfma_f32_16x16x32_f16 v[86:89], v[14:17], v[54:57], v[86:89]
	v_mfma_f32_16x16x32_f16 v[90:93], v[10:13], v[58:61], 0
	v_mfma_f32_16x16x32_f16 v[102:105], v[14:17], v[62:65], v[90:93]
	v_mfma_f32_16x16x32_f16 v[90:93], v[18:21], v[34:37], 0
	v_mfma_f32_16x16x32_f16 v[118:121], v[22:25], v[38:41], v[90:93]
	v_mfma_f32_16x16x32_f16 v[34:37], v[26:29], v[34:37], 0
	v_mfma_f32_16x16x32_f16 v[34:37], v[30:33], v[38:41], v[34:37]
	v_mfma_f32_16x16x32_f16 v[38:41], v[18:21], v[42:45], 0
	v_mfma_f32_16x16x32_f16 v[38:41], v[22:25], v[46:49], v[38:41]
	v_mfma_f32_16x16x32_f16 v[42:45], v[26:29], v[42:45], 0
	v_mfma_f32_16x16x32_f16 v[42:45], v[30:33], v[46:49], v[42:45]
	v_mfma_f32_16x16x32_f16 v[46:49], v[18:21], v[50:53], 0
	v_mfma_f32_16x16x32_f16 v[46:49], v[22:25], v[54:57], v[46:49]
	v_mfma_f32_16x16x32_f16 v[50:53], v[26:29], v[50:53], 0
	v_mfma_f32_16x16x32_f16 v[50:53], v[30:33], v[54:57], v[50:53]
	v_mfma_f32_16x16x32_f16 v[54:57], v[18:21], v[58:61], 0
	v_mfma_f32_16x16x32_f16 v[54:57], v[22:25], v[62:65], v[54:57]
	v_mfma_f32_16x16x32_f16 v[58:61], v[26:29], v[58:61], 0
	v_mfma_f32_16x16x32_f16 v[58:61], v[30:33], v[62:65], v[58:61]
	s_barrier
	s_setprio 0
	ds_read_b128 v[62:65], v212 offset:16384
	ds_read_b128 v[90:93], v212 offset:17408
	ds_read_b128 v[98:101], v212 offset:18432
	ds_read_b128 v[106:109], v212 offset:19456
	ds_read_b128 v[110:113], v212 offset:20480
	ds_read_b128 v[114:117], v212 offset:21504
	ds_read_b128 v[122:125], v212 offset:22528
	ds_read_b128 v[126:129], v212 offset:23552
	s_add_u32 m0, s14, 0x10000
	s_nop 0
	global_load_lds_dwordx4 v207, s[54:55]
	s_nop 0
	s_add_u32 m0, s14, 0x12000
	s_nop 0
	global_load_lds_dwordx4 v209, s[54:55]
	s_add_u32 s54, s6, 0x40100
	s_addc_u32 s55, s7, 0
	s_add_u32 m0, s14, 0x14000
	s_nop 0
	global_load_lds_dwordx4 v207, s[54:55]
	s_nop 0
	s_add_u32 m0, s14, 0x16000
	s_nop 0
	global_load_lds_dwordx4 v209, s[54:55]
	s_nop 0
	s_add_u32 m0, s14, 0
	s_nop 0
	global_load_lds_dwordx4 v206, s[48:49]
	s_nop 0
	s_add_u32 m0, s14, 0x2000
	s_nop 0
	global_load_lds_dwordx4 v208, s[48:49]
	s_waitcnt vmcnt(14)
	s_waitcnt lgkmcnt(0)
	s_barrier
	v_mfma_f32_16x16x32_f16 v[130:133], v[2:5], v[62:65], 0
	s_setprio 1
	v_mfma_f32_16x16x32_f16 v[130:133], v[6:9], v[90:93], v[130:133]
	v_mfma_f32_16x16x32_f16 v[138:141], v[2:5], v[98:101], 0
	v_mfma_f32_16x16x32_f16 v[138:141], v[6:9], v[106:109], v[138:141]
	v_mfma_f32_16x16x32_f16 v[146:149], v[2:5], v[110:113], 0
	v_mfma_f32_16x16x32_f16 v[146:149], v[6:9], v[114:117], v[146:149]
	v_mfma_f32_16x16x32_f16 v[2:5], v[2:5], v[122:125], 0
	v_mfma_f32_16x16x32_f16 v[2:5], v[6:9], v[126:129], v[2:5]
	v_mfma_f32_16x16x32_f16 v[6:9], v[10:13], v[122:125], 0
	v_mfma_f32_16x16x32_f16 v[6:9], v[14:17], v[126:129], v[6:9]
	v_mfma_f32_16x16x32_f16 v[134:137], v[10:13], v[62:65], 0
	v_mfma_f32_16x16x32_f16 v[134:137], v[14:17], v[90:93], v[134:137]
	v_mfma_f32_16x16x32_f16 v[142:145], v[10:13], v[98:101], 0
	v_mfma_f32_16x16x32_f16 v[142:145], v[14:17], v[106:109], v[142:145]
	v_mfma_f32_16x16x32_f16 v[150:153], v[10:13], v[110:113], 0
	v_mfma_f32_16x16x32_f16 v[150:153], v[14:17], v[114:117], v[150:153]
	v_mfma_f32_16x16x32_f16 v[10:13], v[18:21], v[62:65], 0
	v_mfma_f32_16x16x32_f16 v[14:17], v[22:25], v[90:93], v[10:13]
	v_mfma_f32_16x16x32_f16 v[10:13], v[26:29], v[62:65], 0
	v_mfma_f32_16x16x32_f16 v[154:157], v[30:33], v[90:93], v[10:13]
	v_mfma_f32_16x16x32_f16 v[10:13], v[18:21], v[98:101], 0
	v_mfma_f32_16x16x32_f16 v[158:161], v[22:25], v[106:109], v[10:13]
	v_mfma_f32_16x16x32_f16 v[10:13], v[26:29], v[98:101], 0
	v_mfma_f32_16x16x32_f16 v[162:165], v[30:33], v[106:109], v[10:13]
	v_mfma_f32_16x16x32_f16 v[10:13], v[18:21], v[110:113], 0
	v_mfma_f32_16x16x32_f16 v[166:169], v[22:25], v[114:117], v[10:13]
	v_mfma_f32_16x16x32_f16 v[10:13], v[26:29], v[110:113], 0
	v_mfma_f32_16x16x32_f16 v[170:173], v[30:33], v[114:117], v[10:13]
	v_mfma_f32_16x16x32_f16 v[10:13], v[18:21], v[122:125], 0
	v_mfma_f32_16x16x32_f16 v[174:177], v[22:25], v[126:129], v[10:13]
	v_mfma_f32_16x16x32_f16 v[10:13], v[26:29], v[122:125], 0
	v_mfma_f32_16x16x32_f16 v[178:181], v[30:33], v[126:129], v[10:13]
	s_barrier
; #define PG8_STAGE(bufoff, gbase, voff) do { if constexpr (ABL & 1) break; glds16s<(bufoff)>((voff)[0], (const void*)(gbase), ldsbw); glds16s<(bufoff) + 8192>((voff)[1], (const void*)(gbase), ldsbw); } while (0)
; #define PG8_LDA(dst, b, h) do { if constexpr (ABL & 4) break; _Pragma("unroll") for (int m = 0; m < 4; ++m) _Pragma("unroll") for (int k = 0; k < 2; ++k) dst[m][k] = *(const LAS f16x8*)(lds + PG8_SA(b, h) + aoff + m * 2048 + k * 1024); } while (0)
; #define PG8_LDB(dst, b, h) do { if constexpr (ABL & 4) break; _Pragma("unroll") for (int n = 0; n < 2; ++n) _Pragma("unroll") for (int k = 0; k < 2; ++k) dst[n][k] = *(const LAS f16x8*)(lds + PG8_SB(b, h) + boff + n * 2048 + k * 1024); } while (0)
; #define PG8_MMA(ai, bj, At, Bt) do { if constexpr (ABL & 2) break; __builtin_amdgcn_s_setprio(1); _Pragma("unroll") for (int m = 0; m < 4; ++m) _Pragma("unroll") for (int n = 0; n < 2; ++n) _Pragma("unroll") for (int k = 0; k < 2; ++k) \
;         acc[ai][bj][m][n] = __builtin_amdgcn_mfma_f32_16x16x32_f16(Bt[n][k], At[m][k], acc[ai][bj][m][n], 0, 0, 0); __builtin_amdgcn_s_setprio(0); } while (0)
; #define PG8_WAIT_V(n) asm volatile("s_waitcnt vmcnt(" #n ")" ::: "memory")
; #define PG8_WAIT_L(n) asm volatile("s_waitcnt lgkmcnt(" #n ")" ::: "memory")
; #define PG8_BAR __builtin_amdgcn_s_barrier()
; #define PG8_SCHED __builtin_amdgcn_sched_barrier(0)
;     ...
;             PG8_LDB(B0, 1, 0); PG8_LDB(B1, 1, 1); PG8_SCHED; PG8_LDA(At, 1, 0); if (!fin) PG8_STAGE(PG8_SA(0, 1), a2 + hstep, voffA);
;             if (!fin) PG8_WAIT_V(8); else PG8_WAIT_V(0); PG8_WAIT_L(0); PG8_BAR; PG8_MMA(0, 0, At, B0); PG8_MMA(0, 1, At, B1); PG8_BAR; PG8_SCHED;
;             PG8_LDA(At, 1, 1); if (!fin) { PG8_STAGE(PG8_SB(1, 0), b3, voffB); PG8_STAGE(PG8_SB(1, 1), b3 + hstep, voffB); PG8_STAGE(PG8_SA(1, 0), a3, voffA); }
;             if (!fin) PG8_WAIT_V(8); PG8_WAIT_L(0); PG8_BAR; PG8_MMA(1, 0, At, B0); PG8_MMA(1, 1, At, B1); PG8_BAR; PG8_SCHED;
	s_setprio 0
	s_nop 4
	ds_read_b128 v[10:13], v213
	ds_read_b128 v[22:25], v213 offset:1024
	ds_read_b128 v[30:33], v213 offset:2048
	ds_read_b128 v[182:185], v213 offset:3072
	ds_read_b128 v[186:189], v214
	ds_read_b128 v[190:193], v214 offset:1024
	ds_read_b128 v[216:219], v214 offset:2048
	ds_read_b128 v[220:223], v214 offset:3072
	ds_read_b128 v[18:21], v212 offset:32768
	ds_read_b128 v[26:29], v212 offset:33792
	ds_read_b128 v[224:227], v212 offset:34816
	ds_read_b128 v[228:231], v212 offset:35840
	ds_read_b128 v[232:235], v212 offset:36864
	ds_read_b128 v[236:239], v212 offset:37888
	ds_read_b128 v[240:243], v212 offset:38912
	ds_read_b128 v[244:247], v212 offset:39936
	s_add_u32 s8, s8, 0x40100
	s_addc_u32 s9, s9, 0
	s_add_u32 m0, s14, 0x4000
	s_nop 0
	global_load_lds_dwordx4 v206, s[8:9]
	s_nop 0
	s_add_u32 m0, s14, 0x6000
	s_nop 0
	global_load_lds_dwordx4 v208, s[8:9]
	s_waitcnt vmcnt(8)
	s_waitcnt lgkmcnt(0)
	s_barrier
	v_mfma_f32_16x16x32_f16 v[62:65], v[10:13], v[18:21], v[66:69]
	s_setprio 1
	v_mfma_f32_16x16x32_f16 v[114:117], v[22:25], v[26:29], v[62:65]
	v_mfma_f32_16x16x32_f16 v[62:65], v[30:33], v[18:21], v[70:73]
	v_mfma_f32_16x16x32_f16 v[110:113], v[182:185], v[26:29], v[62:65]
	v_mfma_f32_16x16x32_f16 v[62:65], v[10:13], v[224:227], v[74:77]
	v_mfma_f32_16x16x32_f16 v[106:109], v[22:25], v[228:231], v[62:65]
	v_mfma_f32_16x16x32_f16 v[62:65], v[30:33], v[224:227], v[78:81]
	v_mfma_f32_16x16x32_f16 v[98:101], v[182:185], v[228:231], v[62:65]
	v_mfma_f32_16x16x32_f16 v[62:65], v[10:13], v[232:235], v[82:85]
	v_mfma_f32_16x16x32_f16 v[90:93], v[22:25], v[236:239], v[62:65]
	v_mfma_f32_16x16x32_f16 v[62:65], v[30:33], v[232:235], v[86:89]
	v_mfma_f32_16x16x32_f16 v[82:85], v[182:185], v[236:239], v[62:65]
	v_mfma_f32_16x16x32_f16 v[62:65], v[10:13], v[240:243], v[94:97]
	v_mfma_f32_16x16x32_f16 v[74:77], v[22:25], v[244:247], v[62:65]
	v_mfma_f32_16x16x32_f16 v[62:65], v[30:33], v[240:243], v[102:105]
	v_mfma_f32_16x16x32_f16 v[62:65], v[182:185], v[244:247], v[62:65]
	v_mfma_f32_16x16x32_f16 v[66:69], v[186:189], v[18:21], v[118:121]
	v_mfma_f32_16x16x32_f16 v[126:129], v[190:193], v[26:29], v[66:69]
	v_mfma_f32_16x16x32_f16 v[18:21], v[216:219], v[18:21], v[34:37]
	v_mfma_f32_16x16x32_f16 v[122:125], v[220:223], v[26:29], v[18:21]
	v_mfma_f32_16x16x32_f16 v[18:21], v[186:189], v[224:227], v[38:41]
	v_mfma_f32_16x16x32_f16 v[118:121], v[190:193], v[228:231], v[18:21]
	v_mfma_f32_16x16x32_f16 v[18:21], v[216:219], v[224:227], v[42:45]
	v_mfma_f32_16x16x32_f16 v[102:105], v[220:223], v[228:231], v[18:21]
	v_mfma_f32_16x16x32_f16 v[18:21], v[186:189], v[232:235], v[46:49]
	v_mfma_f32_16x16x32_f16 v[94:97], v[190:193], v[236:239], v[18:21]
	v_mfma_f32_16x16x32_f16 v[18:21], v[216:219], v[232:235], v[50:53]
	v_mfma_f32_16x16x32_f16 v[86:89], v[220:223], v[236:239], v[18:21]
	v_mfma_f32_16x16x32_f16 v[18:21], v[186:189], v[240:243], v[54:57]
	v_mfma_f32_16x16x32_f16 v[78:81], v[190:193], v[244:247], v[18:21]
	v_mfma_f32_16x16x32_f16 v[18:21], v[216:219], v[240:243], v[58:61]
	v_mfma_f32_16x16x32_f16 v[70:73], v[220:223], v[244:247], v[18:21]
	s_barrier
	s_setprio 0
	ds_read_b128 v[38:41], v212 offset:49152
	ds_read_b128 v[46:49], v212 offset:50176
	ds_read_b128 v[224:227], v212 offset:51200
	ds_read_b128 v[228:231], v212 offset:52224
	ds_read_b128 v[232:235], v212 offset:53248
	ds_read_b128 v[236:239], v212 offset:54272
	ds_read_b128 v[240:243], v212 offset:55296
	ds_read_b128 v[244:247], v212 offset:56320
	s_add_u32 m0, s14, 0x18000
	s_nop 0
	global_load_lds_dwordx4 v207, s[26:27]
	s_nop 0
	s_add_u32 m0, s14, 0x1a000
	s_nop 0
	global_load_lds_dwordx4 v209, s[26:27]
	s_add_u32 s8, s6, 0x40180
	s_addc_u32 s9, s7, 0
	s_add_u32 m0, s14, 0x1c000
	s_nop 0
	global_load_lds_dwordx4 v207, s[8:9]
	s_nop 0
	s_add_u32 m0, s14, 0x1e000
	s_nop 0
	global_load_lds_dwordx4 v209, s[8:9]
	s_nop 0
	s_add_u32 m0, s14, 0x8000
	s_nop 0
	global_load_lds_dwordx4 v206, s[24:25]
	s_nop 0
	s_add_u32 m0, s14, 0xa000
	s_nop 0
	global_load_lds_dwordx4 v208, s[24:25]
	s_waitcnt vmcnt(8)
	s_waitcnt lgkmcnt(0)
	s_barrier
	v_mfma_f32_16x16x32_f16 v[18:21], v[10:13], v[38:41], v[130:133]
	s_setprio 1
	v_mfma_f32_16x16x32_f16 v[58:61], v[22:25], v[46:49], v[18:21]
	v_mfma_f32_16x16x32_f16 v[18:21], v[182:185], v[46:49], v[134:137]
	v_mfma_f32_16x16x32_f16 v[50:53], v[30:33], v[38:41], v[18:21]
	v_mfma_f32_16x16x32_f16 v[18:21], v[10:13], v[224:227], v[138:141]
	v_mfma_f32_16x16x32_f16 v[42:45], v[22:25], v[228:231], v[18:21]
	v_mfma_f32_16x16x32_f16 v[18:21], v[182:185], v[228:231], v[142:145]
	v_mfma_f32_16x16x32_f16 v[34:37], v[30:33], v[224:227], v[18:21]
	v_mfma_f32_16x16x32_f16 v[18:21], v[10:13], v[232:235], v[146:149]
	v_mfma_f32_16x16x32_f16 v[26:29], v[22:25], v[236:239], v[18:21]
	v_mfma_f32_16x16x32_f16 v[2:5], v[22:25], v[244:247], v[2:5]
	v_mfma_f32_16x16x32_f16 v[10:13], v[10:13], v[240:243], v[2:5]
	v_mfma_f32_16x16x32_f16 v[2:5], v[30:33], v[240:243], v[6:9]
	v_mfma_f32_16x16x32_f16 v[2:5], v[182:185], v[244:247], v[2:5]
	v_mfma_f32_16x16x32_f16 v[18:21], v[182:185], v[236:239], v[150:153]
	v_mfma_f32_16x16x32_f16 v[18:21], v[30:33], v[232:235], v[18:21]
	v_mfma_f32_16x16x32_f16 v[6:9], v[186:189], v[38:41], v[14:17]
	v_mfma_f32_16x16x32_f16 v[66:69], v[190:193], v[46:49], v[6:9]
	v_mfma_f32_16x16x32_f16 v[6:9], v[220:223], v[46:49], v[154:157]
	v_mfma_f32_16x16x32_f16 v[54:57], v[216:219], v[38:41], v[6:9]
	v_mfma_f32_16x16x32_f16 v[6:9], v[186:189], v[224:227], v[158:161]
	v_mfma_f32_16x16x32_f16 v[46:49], v[190:193], v[228:231], v[6:9]
	v_mfma_f32_16x16x32_f16 v[6:9], v[220:223], v[228:231], v[162:165]
	v_mfma_f32_16x16x32_f16 v[38:41], v[216:219], v[224:227], v[6:9]
	v_mfma_f32_16x16x32_f16 v[6:9], v[186:189], v[232:235], v[166:169]
	v_mfma_f32_16x16x32_f16 v[30:33], v[190:193], v[236:239], v[6:9]
	v_mfma_f32_16x16x32_f16 v[6:9], v[220:223], v[236:239], v[170:173]
	v_mfma_f32_16x16x32_f16 v[22:25], v[216:219], v[232:235], v[6:9]
	v_mfma_f32_16x16x32_f16 v[6:9], v[186:189], v[240:243], v[174:177]
	v_mfma_f32_16x16x32_f16 v[14:17], v[190:193], v[244:247], v[6:9]
	v_mfma_f32_16x16x32_f16 v[6:9], v[220:223], v[244:247], v[178:181]
	v_mfma_f32_16x16x32_f16 v[6:9], v[216:219], v[240:243], v[6:9]
	s_barrier
	s_setprio 0
	s_add_u32 s53, s6, 0x200
	s_addc_u32 s54, s7, 0
	s_mov_b32 s55, 0
	s_branch .LBB0_843
